# speedup vs baseline: 1.0063x; 1.0063x over previous
; __device__ __forceinline__ void phase0(const Params& p, char* smem) {
;     ...
;         for (int i = lane; i < 33 * 128; i += 64) {
;           int b = i >> 7, k = i & 127;
;           float cv = b < 32 ? p.c[b * 1024 + kbase + k] : p.c_ctx[kbase + k];
;           scw[i] = cv / (1.f + __expf(-cv));
.LBB0_1942:
	s_xor_b64 s[16:17], s[18:19], -1
	v_or_b32_e32 v4, s7, v1
	s_mov_b64 s[18:19], 0
	v_mov_b32_e32 v5, v74
	v_mov_b32_e32 v6, v73
	v_mov_b32_e32 v7, v16
	s_barrier
	v_or_b32_e32 v166, v4, v16
	v_lshlrev_b32_e32 v166, 2, v166
	s_mov_b32 s44, s30
	s_mov_b32 s45, s31
	global_load_dword v100, v166, s[44:45]
	global_load_dword v101, v166, s[44:45] offset:256
	s_add_u32 s44, s30, 0x1000
	s_addc_u32 s45, s31, 0
	global_load_dword v102, v166, s[44:45]
	global_load_dword v103, v166, s[44:45] offset:256
	s_add_u32 s44, s30, 0x2000
	s_addc_u32 s45, s31, 0
	global_load_dword v104, v166, s[44:45]
	global_load_dword v105, v166, s[44:45] offset:256
	s_add_u32 s44, s30, 0x3000
	s_addc_u32 s45, s31, 0
	global_load_dword v106, v166, s[44:45]
	global_load_dword v107, v166, s[44:45] offset:256
	s_add_u32 s44, s30, 0x4000
	s_addc_u32 s45, s31, 0
	global_load_dword v108, v166, s[44:45]
	global_load_dword v109, v166, s[44:45] offset:256
	s_add_u32 s44, s30, 0x5000
	s_addc_u32 s45, s31, 0
	global_load_dword v110, v166, s[44:45]
	global_load_dword v111, v166, s[44:45] offset:256
	s_add_u32 s44, s30, 0x6000
	s_addc_u32 s45, s31, 0
	global_load_dword v112, v166, s[44:45]
	global_load_dword v113, v166, s[44:45] offset:256
	s_add_u32 s44, s30, 0x7000
	s_addc_u32 s45, s31, 0
	global_load_dword v114, v166, s[44:45]
	global_load_dword v115, v166, s[44:45] offset:256
	s_add_u32 s44, s30, 0x8000
	s_addc_u32 s45, s31, 0
	global_load_dword v116, v166, s[44:45]
	global_load_dword v117, v166, s[44:45] offset:256
	s_add_u32 s44, s30, 0x9000
	s_addc_u32 s45, s31, 0
	global_load_dword v118, v166, s[44:45]
	global_load_dword v119, v166, s[44:45] offset:256
	s_add_u32 s44, s30, 0xa000
	s_addc_u32 s45, s31, 0
	global_load_dword v120, v166, s[44:45]
	global_load_dword v121, v166, s[44:45] offset:256
	s_add_u32 s44, s30, 0xb000
	s_addc_u32 s45, s31, 0
	global_load_dword v122, v166, s[44:45]
	global_load_dword v123, v166, s[44:45] offset:256
	s_add_u32 s44, s30, 0xc000
	s_addc_u32 s45, s31, 0
	global_load_dword v124, v166, s[44:45]
	global_load_dword v125, v166, s[44:45] offset:256
	s_add_u32 s44, s30, 0xd000
	s_addc_u32 s45, s31, 0
	global_load_dword v126, v166, s[44:45]
	global_load_dword v127, v166, s[44:45] offset:256
	s_add_u32 s44, s30, 0xe000
	s_addc_u32 s45, s31, 0
	global_load_dword v128, v166, s[44:45]
	global_load_dword v129, v166, s[44:45] offset:256
	s_add_u32 s44, s30, 0xf000
	s_addc_u32 s45, s31, 0
	global_load_dword v130, v166, s[44:45]
	global_load_dword v131, v166, s[44:45] offset:256
	s_add_u32 s44, s30, 0x10000
	s_addc_u32 s45, s31, 0
	global_load_dword v132, v166, s[44:45]
	global_load_dword v133, v166, s[44:45] offset:256
	s_add_u32 s44, s30, 0x11000
	s_addc_u32 s45, s31, 0
	global_load_dword v134, v166, s[44:45]
	global_load_dword v135, v166, s[44:45] offset:256
	s_add_u32 s44, s30, 0x12000
	s_addc_u32 s45, s31, 0
	global_load_dword v136, v166, s[44:45]
	global_load_dword v137, v166, s[44:45] offset:256
	s_add_u32 s44, s30, 0x13000
	s_addc_u32 s45, s31, 0
	global_load_dword v138, v166, s[44:45]
	global_load_dword v139, v166, s[44:45] offset:256
	s_add_u32 s44, s30, 0x14000
	s_addc_u32 s45, s31, 0
	global_load_dword v140, v166, s[44:45]
	global_load_dword v141, v166, s[44:45] offset:256
	s_add_u32 s44, s30, 0x15000
	s_addc_u32 s45, s31, 0
	global_load_dword v142, v166, s[44:45]
	global_load_dword v143, v166, s[44:45] offset:256
	s_add_u32 s44, s30, 0x16000
	s_addc_u32 s45, s31, 0
	global_load_dword v144, v166, s[44:45]
	global_load_dword v145, v166, s[44:45] offset:256
	s_add_u32 s44, s30, 0x17000
	s_addc_u32 s45, s31, 0
	global_load_dword v146, v166, s[44:45]
	global_load_dword v147, v166, s[44:45] offset:256
	s_add_u32 s44, s30, 0x18000
	s_addc_u32 s45, s31, 0
	global_load_dword v148, v166, s[44:45]
	global_load_dword v149, v166, s[44:45] offset:256
	s_add_u32 s44, s30, 0x19000
	s_addc_u32 s45, s31, 0
	global_load_dword v150, v166, s[44:45]
	global_load_dword v151, v166, s[44:45] offset:256
	s_add_u32 s44, s30, 0x1a000
	s_addc_u32 s45, s31, 0
	global_load_dword v152, v166, s[44:45]
	global_load_dword v153, v166, s[44:45] offset:256
	s_add_u32 s44, s30, 0x1b000
	s_addc_u32 s45, s31, 0
	global_load_dword v154, v166, s[44:45]
	global_load_dword v155, v166, s[44:45] offset:256
	s_add_u32 s44, s30, 0x1c000
	s_addc_u32 s45, s31, 0
	global_load_dword v156, v166, s[44:45]
	global_load_dword v157, v166, s[44:45] offset:256
	s_add_u32 s44, s30, 0x1d000
	s_addc_u32 s45, s31, 0
	global_load_dword v158, v166, s[44:45]
	global_load_dword v159, v166, s[44:45] offset:256
	s_add_u32 s44, s30, 0x1e000
	s_addc_u32 s45, s31, 0
	global_load_dword v160, v166, s[44:45]
	global_load_dword v161, v166, s[44:45] offset:256
	s_add_u32 s44, s30, 0x1f000
	s_addc_u32 s45, s31, 0
	global_load_dword v162, v166, s[44:45]
	global_load_dword v163, v166, s[44:45] offset:256
	global_load_dword v164, v166, s[12:13]
	global_load_dword v165, v166, s[12:13] offset:256
	s_waitcnt vmcnt(0)
; __device__ __forceinline__ void phase0(const Params& p, char* smem) {
;     ...
;           float cv = b < 32 ? p.c[b * 1024 + kbase + k] : p.c_ctx[kbase + k];
;           scw[i] = cv / (1.f + __expf(-cv));
	v_mul_f32_e32 v3, 0xbfb8aa3b, v100
	v_exp_f32_e32 v3, v3
	s_nop 0
	v_add_f32_e32 v3, 1.0, v3
	v_div_scale_f32 v7, s[44:45], v3, v3, v100
	v_rcp_f32_e32 v9, v7
	v_div_scale_f32 v10, vcc, v100, v3, v100
	v_fma_f32 v11, -v7, v9, 1.0
	v_fmac_f32_e32 v9, v11, v9
	v_mul_f32_e32 v11, v10, v9
	v_fma_f32 v12, -v7, v11, v10
	v_fmac_f32_e32 v11, v12, v9
	v_fma_f32 v7, -v7, v11, v10
	v_div_fmas_f32 v7, v7, v9, v11
	v_div_fixup_f32 v2, v7, v3, v100
	ds_write_b32 v5, v2
	v_mul_f32_e32 v3, 0xbfb8aa3b, v101
	v_exp_f32_e32 v3, v3
	s_nop 0
	v_add_f32_e32 v3, 1.0, v3
	v_div_scale_f32 v7, s[44:45], v3, v3, v101
	v_rcp_f32_e32 v9, v7
	v_div_scale_f32 v10, vcc, v101, v3, v101
	v_fma_f32 v11, -v7, v9, 1.0
	v_fmac_f32_e32 v9, v11, v9
	v_mul_f32_e32 v11, v10, v9
	v_fma_f32 v12, -v7, v11, v10
	v_fmac_f32_e32 v11, v12, v9
	v_fma_f32 v7, -v7, v11, v10
	v_div_fmas_f32 v7, v7, v9, v11
	v_div_fixup_f32 v2, v7, v3, v101
	ds_write_b32 v5, v2 offset:256
	v_mul_f32_e32 v3, 0xbfb8aa3b, v102
	v_exp_f32_e32 v3, v3
	s_nop 0
	v_add_f32_e32 v3, 1.0, v3
	v_div_scale_f32 v7, s[44:45], v3, v3, v102
	v_rcp_f32_e32 v9, v7
	v_div_scale_f32 v10, vcc, v102, v3, v102
	v_fma_f32 v11, -v7, v9, 1.0
	v_fmac_f32_e32 v9, v11, v9
	v_mul_f32_e32 v11, v10, v9
	v_fma_f32 v12, -v7, v11, v10
	v_fmac_f32_e32 v11, v12, v9
	v_fma_f32 v7, -v7, v11, v10
	v_div_fmas_f32 v7, v7, v9, v11
	v_div_fixup_f32 v2, v7, v3, v102
	ds_write_b32 v5, v2 offset:512
	v_mul_f32_e32 v3, 0xbfb8aa3b, v103
	v_exp_f32_e32 v3, v3
	s_nop 0
	v_add_f32_e32 v3, 1.0, v3
	v_div_scale_f32 v7, s[44:45], v3, v3, v103
	v_rcp_f32_e32 v9, v7
	v_div_scale_f32 v10, vcc, v103, v3, v103
	v_fma_f32 v11, -v7, v9, 1.0
	v_fmac_f32_e32 v9, v11, v9
	v_mul_f32_e32 v11, v10, v9
	v_fma_f32 v12, -v7, v11, v10
	v_fmac_f32_e32 v11, v12, v9
	v_fma_f32 v7, -v7, v11, v10
	v_div_fmas_f32 v7, v7, v9, v11
	v_div_fixup_f32 v2, v7, v3, v103
	ds_write_b32 v5, v2 offset:768
	v_mul_f32_e32 v3, 0xbfb8aa3b, v104
	v_exp_f32_e32 v3, v3
	s_nop 0
	v_add_f32_e32 v3, 1.0, v3
	v_div_scale_f32 v7, s[44:45], v3, v3, v104
	v_rcp_f32_e32 v9, v7
	v_div_scale_f32 v10, vcc, v104, v3, v104
	v_fma_f32 v11, -v7, v9, 1.0
	v_fmac_f32_e32 v9, v11, v9
	v_mul_f32_e32 v11, v10, v9
	v_fma_f32 v12, -v7, v11, v10
	v_fmac_f32_e32 v11, v12, v9
	v_fma_f32 v7, -v7, v11, v10
	v_div_fmas_f32 v7, v7, v9, v11
	v_div_fixup_f32 v2, v7, v3, v104
	ds_write_b32 v5, v2 offset:1024
	v_mul_f32_e32 v3, 0xbfb8aa3b, v105
	v_exp_f32_e32 v3, v3
	s_nop 0
	v_add_f32_e32 v3, 1.0, v3
	v_div_scale_f32 v7, s[44:45], v3, v3, v105
	v_rcp_f32_e32 v9, v7
	v_div_scale_f32 v10, vcc, v105, v3, v105
	v_fma_f32 v11, -v7, v9, 1.0
	v_fmac_f32_e32 v9, v11, v9
	v_mul_f32_e32 v11, v10, v9
	v_fma_f32 v12, -v7, v11, v10
	v_fmac_f32_e32 v11, v12, v9
	v_fma_f32 v7, -v7, v11, v10
	v_div_fmas_f32 v7, v7, v9, v11
	v_div_fixup_f32 v2, v7, v3, v105
	ds_write_b32 v5, v2 offset:1280
	v_mul_f32_e32 v3, 0xbfb8aa3b, v106
	v_exp_f32_e32 v3, v3
	s_nop 0
	v_add_f32_e32 v3, 1.0, v3
	v_div_scale_f32 v7, s[44:45], v3, v3, v106
	v_rcp_f32_e32 v9, v7
	v_div_scale_f32 v10, vcc, v106, v3, v106
	v_fma_f32 v11, -v7, v9, 1.0
	v_fmac_f32_e32 v9, v11, v9
	v_mul_f32_e32 v11, v10, v9
	v_fma_f32 v12, -v7, v11, v10
	v_fmac_f32_e32 v11, v12, v9
	v_fma_f32 v7, -v7, v11, v10
	v_div_fmas_f32 v7, v7, v9, v11
	v_div_fixup_f32 v2, v7, v3, v106
	ds_write_b32 v5, v2 offset:1536
	v_mul_f32_e32 v3, 0xbfb8aa3b, v107
	v_exp_f32_e32 v3, v3
	s_nop 0
	v_add_f32_e32 v3, 1.0, v3
	v_div_scale_f32 v7, s[44:45], v3, v3, v107
	v_rcp_f32_e32 v9, v7
	v_div_scale_f32 v10, vcc, v107, v3, v107
	v_fma_f32 v11, -v7, v9, 1.0
	v_fmac_f32_e32 v9, v11, v9
	v_mul_f32_e32 v11, v10, v9
	v_fma_f32 v12, -v7, v11, v10
	v_fmac_f32_e32 v11, v12, v9
	v_fma_f32 v7, -v7, v11, v10
	v_div_fmas_f32 v7, v7, v9, v11
	v_div_fixup_f32 v2, v7, v3, v107
	ds_write_b32 v5, v2 offset:1792
	v_mul_f32_e32 v3, 0xbfb8aa3b, v108
	v_exp_f32_e32 v3, v3
	s_nop 0
	v_add_f32_e32 v3, 1.0, v3
	v_div_scale_f32 v7, s[44:45], v3, v3, v108
	v_rcp_f32_e32 v9, v7
	v_div_scale_f32 v10, vcc, v108, v3, v108
	v_fma_f32 v11, -v7, v9, 1.0
	v_fmac_f32_e32 v9, v11, v9
	v_mul_f32_e32 v11, v10, v9
	v_fma_f32 v12, -v7, v11, v10
	v_fmac_f32_e32 v11, v12, v9
	v_fma_f32 v7, -v7, v11, v10
	v_div_fmas_f32 v7, v7, v9, v11
	v_div_fixup_f32 v2, v7, v3, v108
	ds_write_b32 v5, v2 offset:2048
	v_mul_f32_e32 v3, 0xbfb8aa3b, v109
	v_exp_f32_e32 v3, v3
	s_nop 0
	v_add_f32_e32 v3, 1.0, v3
	v_div_scale_f32 v7, s[44:45], v3, v3, v109
	v_rcp_f32_e32 v9, v7
	v_div_scale_f32 v10, vcc, v109, v3, v109
	v_fma_f32 v11, -v7, v9, 1.0
	v_fmac_f32_e32 v9, v11, v9
	v_mul_f32_e32 v11, v10, v9
	v_fma_f32 v12, -v7, v11, v10
	v_fmac_f32_e32 v11, v12, v9
	v_fma_f32 v7, -v7, v11, v10
	v_div_fmas_f32 v7, v7, v9, v11
	v_div_fixup_f32 v2, v7, v3, v109
	ds_write_b32 v5, v2 offset:2304
	v_mul_f32_e32 v3, 0xbfb8aa3b, v110
	v_exp_f32_e32 v3, v3
	s_nop 0
	v_add_f32_e32 v3, 1.0, v3
	v_div_scale_f32 v7, s[44:45], v3, v3, v110
	v_rcp_f32_e32 v9, v7
	v_div_scale_f32 v10, vcc, v110, v3, v110
	v_fma_f32 v11, -v7, v9, 1.0
	v_fmac_f32_e32 v9, v11, v9
	v_mul_f32_e32 v11, v10, v9
	v_fma_f32 v12, -v7, v11, v10
	v_fmac_f32_e32 v11, v12, v9
	v_fma_f32 v7, -v7, v11, v10
	v_div_fmas_f32 v7, v7, v9, v11
	v_div_fixup_f32 v2, v7, v3, v110
	ds_write_b32 v5, v2 offset:2560
	v_mul_f32_e32 v3, 0xbfb8aa3b, v111
	v_exp_f32_e32 v3, v3
	s_nop 0
	v_add_f32_e32 v3, 1.0, v3
	v_div_scale_f32 v7, s[44:45], v3, v3, v111
	v_rcp_f32_e32 v9, v7
	v_div_scale_f32 v10, vcc, v111, v3, v111
	v_fma_f32 v11, -v7, v9, 1.0
	v_fmac_f32_e32 v9, v11, v9
	v_mul_f32_e32 v11, v10, v9
	v_fma_f32 v12, -v7, v11, v10
	v_fmac_f32_e32 v11, v12, v9
	v_fma_f32 v7, -v7, v11, v10
	v_div_fmas_f32 v7, v7, v9, v11
	v_div_fixup_f32 v2, v7, v3, v111
; __device__ __forceinline__ void phase0(const Params& p, char* smem) {
;     ...
;           float cv = b < 32 ? p.c[b * 1024 + kbase + k] : p.c_ctx[kbase + k];
;           scw[i] = cv / (1.f + __expf(-cv));
	ds_write_b32 v5, v2 offset:2816
	v_mul_f32_e32 v3, 0xbfb8aa3b, v112
	v_exp_f32_e32 v3, v3
	s_nop 0
	v_add_f32_e32 v3, 1.0, v3
	v_div_scale_f32 v7, s[44:45], v3, v3, v112
	v_rcp_f32_e32 v9, v7
	v_div_scale_f32 v10, vcc, v112, v3, v112
	v_fma_f32 v11, -v7, v9, 1.0
	v_fmac_f32_e32 v9, v11, v9
	v_mul_f32_e32 v11, v10, v9
	v_fma_f32 v12, -v7, v11, v10
	v_fmac_f32_e32 v11, v12, v9
	v_fma_f32 v7, -v7, v11, v10
	v_div_fmas_f32 v7, v7, v9, v11
	v_div_fixup_f32 v2, v7, v3, v112
	ds_write_b32 v5, v2 offset:3072
	v_mul_f32_e32 v3, 0xbfb8aa3b, v113
	v_exp_f32_e32 v3, v3
	s_nop 0
	v_add_f32_e32 v3, 1.0, v3
	v_div_scale_f32 v7, s[44:45], v3, v3, v113
	v_rcp_f32_e32 v9, v7
	v_div_scale_f32 v10, vcc, v113, v3, v113
	v_fma_f32 v11, -v7, v9, 1.0
	v_fmac_f32_e32 v9, v11, v9
	v_mul_f32_e32 v11, v10, v9
	v_fma_f32 v12, -v7, v11, v10
	v_fmac_f32_e32 v11, v12, v9
	v_fma_f32 v7, -v7, v11, v10
	v_div_fmas_f32 v7, v7, v9, v11
	v_div_fixup_f32 v2, v7, v3, v113
	ds_write_b32 v5, v2 offset:3328
	v_mul_f32_e32 v3, 0xbfb8aa3b, v114
	v_exp_f32_e32 v3, v3
	s_nop 0
	v_add_f32_e32 v3, 1.0, v3
	v_div_scale_f32 v7, s[44:45], v3, v3, v114
	v_rcp_f32_e32 v9, v7
	v_div_scale_f32 v10, vcc, v114, v3, v114
	v_fma_f32 v11, -v7, v9, 1.0
	v_fmac_f32_e32 v9, v11, v9
	v_mul_f32_e32 v11, v10, v9
	v_fma_f32 v12, -v7, v11, v10
	v_fmac_f32_e32 v11, v12, v9
	v_fma_f32 v7, -v7, v11, v10
	v_div_fmas_f32 v7, v7, v9, v11
	v_div_fixup_f32 v2, v7, v3, v114
	ds_write_b32 v5, v2 offset:3584
	v_mul_f32_e32 v3, 0xbfb8aa3b, v115
	v_exp_f32_e32 v3, v3
	s_nop 0
	v_add_f32_e32 v3, 1.0, v3
	v_div_scale_f32 v7, s[44:45], v3, v3, v115
	v_rcp_f32_e32 v9, v7
	v_div_scale_f32 v10, vcc, v115, v3, v115
	v_fma_f32 v11, -v7, v9, 1.0
	v_fmac_f32_e32 v9, v11, v9
	v_mul_f32_e32 v11, v10, v9
	v_fma_f32 v12, -v7, v11, v10
	v_fmac_f32_e32 v11, v12, v9
	v_fma_f32 v7, -v7, v11, v10
	v_div_fmas_f32 v7, v7, v9, v11
	v_div_fixup_f32 v2, v7, v3, v115
	ds_write_b32 v5, v2 offset:3840
	v_mul_f32_e32 v3, 0xbfb8aa3b, v116
	v_exp_f32_e32 v3, v3
	s_nop 0
	v_add_f32_e32 v3, 1.0, v3
	v_div_scale_f32 v7, s[44:45], v3, v3, v116
	v_rcp_f32_e32 v9, v7
	v_div_scale_f32 v10, vcc, v116, v3, v116
	v_fma_f32 v11, -v7, v9, 1.0
	v_fmac_f32_e32 v9, v11, v9
	v_mul_f32_e32 v11, v10, v9
	v_fma_f32 v12, -v7, v11, v10
	v_fmac_f32_e32 v11, v12, v9
	v_fma_f32 v7, -v7, v11, v10
	v_div_fmas_f32 v7, v7, v9, v11
	v_div_fixup_f32 v2, v7, v3, v116
	ds_write_b32 v5, v2 offset:4096
	v_mul_f32_e32 v3, 0xbfb8aa3b, v117
	v_exp_f32_e32 v3, v3
	s_nop 0
	v_add_f32_e32 v3, 1.0, v3
	v_div_scale_f32 v7, s[44:45], v3, v3, v117
	v_rcp_f32_e32 v9, v7
	v_div_scale_f32 v10, vcc, v117, v3, v117
	v_fma_f32 v11, -v7, v9, 1.0
	v_fmac_f32_e32 v9, v11, v9
	v_mul_f32_e32 v11, v10, v9
	v_fma_f32 v12, -v7, v11, v10
	v_fmac_f32_e32 v11, v12, v9
	v_fma_f32 v7, -v7, v11, v10
	v_div_fmas_f32 v7, v7, v9, v11
	v_div_fixup_f32 v2, v7, v3, v117
	ds_write_b32 v5, v2 offset:4352
	v_mul_f32_e32 v3, 0xbfb8aa3b, v118
	v_exp_f32_e32 v3, v3
	s_nop 0
	v_add_f32_e32 v3, 1.0, v3
	v_div_scale_f32 v7, s[44:45], v3, v3, v118
	v_rcp_f32_e32 v9, v7
	v_div_scale_f32 v10, vcc, v118, v3, v118
	v_fma_f32 v11, -v7, v9, 1.0
	v_fmac_f32_e32 v9, v11, v9
	v_mul_f32_e32 v11, v10, v9
	v_fma_f32 v12, -v7, v11, v10
	v_fmac_f32_e32 v11, v12, v9
	v_fma_f32 v7, -v7, v11, v10
	v_div_fmas_f32 v7, v7, v9, v11
	v_div_fixup_f32 v2, v7, v3, v118
	ds_write_b32 v5, v2 offset:4608
	v_mul_f32_e32 v3, 0xbfb8aa3b, v119
	v_exp_f32_e32 v3, v3
	s_nop 0
	v_add_f32_e32 v3, 1.0, v3
	v_div_scale_f32 v7, s[44:45], v3, v3, v119
	v_rcp_f32_e32 v9, v7
	v_div_scale_f32 v10, vcc, v119, v3, v119
	v_fma_f32 v11, -v7, v9, 1.0
	v_fmac_f32_e32 v9, v11, v9
	v_mul_f32_e32 v11, v10, v9
	v_fma_f32 v12, -v7, v11, v10
	v_fmac_f32_e32 v11, v12, v9
	v_fma_f32 v7, -v7, v11, v10
	v_div_fmas_f32 v7, v7, v9, v11
	v_div_fixup_f32 v2, v7, v3, v119
	ds_write_b32 v5, v2 offset:4864
	v_mul_f32_e32 v3, 0xbfb8aa3b, v120
	v_exp_f32_e32 v3, v3
	s_nop 0
	v_add_f32_e32 v3, 1.0, v3
	v_div_scale_f32 v7, s[44:45], v3, v3, v120
	v_rcp_f32_e32 v9, v7
	v_div_scale_f32 v10, vcc, v120, v3, v120
	v_fma_f32 v11, -v7, v9, 1.0
	v_fmac_f32_e32 v9, v11, v9
	v_mul_f32_e32 v11, v10, v9
	v_fma_f32 v12, -v7, v11, v10
	v_fmac_f32_e32 v11, v12, v9
	v_fma_f32 v7, -v7, v11, v10
	v_div_fmas_f32 v7, v7, v9, v11
	v_div_fixup_f32 v2, v7, v3, v120
	ds_write_b32 v5, v2 offset:5120
	v_mul_f32_e32 v3, 0xbfb8aa3b, v121
	v_exp_f32_e32 v3, v3
	s_nop 0
	v_add_f32_e32 v3, 1.0, v3
	v_div_scale_f32 v7, s[44:45], v3, v3, v121
	v_rcp_f32_e32 v9, v7
	v_div_scale_f32 v10, vcc, v121, v3, v121
	v_fma_f32 v11, -v7, v9, 1.0
	v_fmac_f32_e32 v9, v11, v9
	v_mul_f32_e32 v11, v10, v9
	v_fma_f32 v12, -v7, v11, v10
	v_fmac_f32_e32 v11, v12, v9
	v_fma_f32 v7, -v7, v11, v10
	v_div_fmas_f32 v7, v7, v9, v11
	v_div_fixup_f32 v2, v7, v3, v121
	ds_write_b32 v5, v2 offset:5376
	v_mul_f32_e32 v3, 0xbfb8aa3b, v122
	v_exp_f32_e32 v3, v3
	s_nop 0
	v_add_f32_e32 v3, 1.0, v3
	v_div_scale_f32 v7, s[44:45], v3, v3, v122
	v_rcp_f32_e32 v9, v7
	v_div_scale_f32 v10, vcc, v122, v3, v122
	v_fma_f32 v11, -v7, v9, 1.0
	v_fmac_f32_e32 v9, v11, v9
	v_mul_f32_e32 v11, v10, v9
	v_fma_f32 v12, -v7, v11, v10
	v_fmac_f32_e32 v11, v12, v9
	v_fma_f32 v7, -v7, v11, v10
	v_div_fmas_f32 v7, v7, v9, v11
	v_div_fixup_f32 v2, v7, v3, v122
	ds_write_b32 v5, v2 offset:5632
	v_mul_f32_e32 v3, 0xbfb8aa3b, v123
	v_exp_f32_e32 v3, v3
	s_nop 0
	v_add_f32_e32 v3, 1.0, v3
	v_div_scale_f32 v7, s[44:45], v3, v3, v123
	v_rcp_f32_e32 v9, v7
	v_div_scale_f32 v10, vcc, v123, v3, v123
	v_fma_f32 v11, -v7, v9, 1.0
	v_fmac_f32_e32 v9, v11, v9
	v_mul_f32_e32 v11, v10, v9
	v_fma_f32 v12, -v7, v11, v10
	v_fmac_f32_e32 v11, v12, v9
	v_fma_f32 v7, -v7, v11, v10
	v_div_fmas_f32 v7, v7, v9, v11
; __device__ __forceinline__ void phase0(const Params& p, char* smem) {
;     ...
;           float cv = b < 32 ? p.c[b * 1024 + kbase + k] : p.c_ctx[kbase + k];
;           scw[i] = cv / (1.f + __expf(-cv));
	v_div_fixup_f32 v2, v7, v3, v123
	ds_write_b32 v5, v2 offset:5888
	v_mul_f32_e32 v3, 0xbfb8aa3b, v124
	v_exp_f32_e32 v3, v3
	s_nop 0
	v_add_f32_e32 v3, 1.0, v3
	v_div_scale_f32 v7, s[44:45], v3, v3, v124
	v_rcp_f32_e32 v9, v7
	v_div_scale_f32 v10, vcc, v124, v3, v124
	v_fma_f32 v11, -v7, v9, 1.0
	v_fmac_f32_e32 v9, v11, v9
	v_mul_f32_e32 v11, v10, v9
	v_fma_f32 v12, -v7, v11, v10
	v_fmac_f32_e32 v11, v12, v9
	v_fma_f32 v7, -v7, v11, v10
	v_div_fmas_f32 v7, v7, v9, v11
	v_div_fixup_f32 v2, v7, v3, v124
	ds_write_b32 v5, v2 offset:6144
	v_mul_f32_e32 v3, 0xbfb8aa3b, v125
	v_exp_f32_e32 v3, v3
	s_nop 0
	v_add_f32_e32 v3, 1.0, v3
	v_div_scale_f32 v7, s[44:45], v3, v3, v125
	v_rcp_f32_e32 v9, v7
	v_div_scale_f32 v10, vcc, v125, v3, v125
	v_fma_f32 v11, -v7, v9, 1.0
	v_fmac_f32_e32 v9, v11, v9
	v_mul_f32_e32 v11, v10, v9
	v_fma_f32 v12, -v7, v11, v10
	v_fmac_f32_e32 v11, v12, v9
	v_fma_f32 v7, -v7, v11, v10
	v_div_fmas_f32 v7, v7, v9, v11
	v_div_fixup_f32 v2, v7, v3, v125
	ds_write_b32 v5, v2 offset:6400
	v_mul_f32_e32 v3, 0xbfb8aa3b, v126
	v_exp_f32_e32 v3, v3
	s_nop 0
	v_add_f32_e32 v3, 1.0, v3
	v_div_scale_f32 v7, s[44:45], v3, v3, v126
	v_rcp_f32_e32 v9, v7
	v_div_scale_f32 v10, vcc, v126, v3, v126
	v_fma_f32 v11, -v7, v9, 1.0
	v_fmac_f32_e32 v9, v11, v9
	v_mul_f32_e32 v11, v10, v9
	v_fma_f32 v12, -v7, v11, v10
	v_fmac_f32_e32 v11, v12, v9
	v_fma_f32 v7, -v7, v11, v10
	v_div_fmas_f32 v7, v7, v9, v11
	v_div_fixup_f32 v2, v7, v3, v126
	ds_write_b32 v5, v2 offset:6656
	v_mul_f32_e32 v3, 0xbfb8aa3b, v127
	v_exp_f32_e32 v3, v3
	s_nop 0
	v_add_f32_e32 v3, 1.0, v3
	v_div_scale_f32 v7, s[44:45], v3, v3, v127
	v_rcp_f32_e32 v9, v7
	v_div_scale_f32 v10, vcc, v127, v3, v127
	v_fma_f32 v11, -v7, v9, 1.0
	v_fmac_f32_e32 v9, v11, v9
	v_mul_f32_e32 v11, v10, v9
	v_fma_f32 v12, -v7, v11, v10
	v_fmac_f32_e32 v11, v12, v9
	v_fma_f32 v7, -v7, v11, v10
	v_div_fmas_f32 v7, v7, v9, v11
	v_div_fixup_f32 v2, v7, v3, v127
	ds_write_b32 v5, v2 offset:6912
	v_mul_f32_e32 v3, 0xbfb8aa3b, v128
	v_exp_f32_e32 v3, v3
	s_nop 0
	v_add_f32_e32 v3, 1.0, v3
	v_div_scale_f32 v7, s[44:45], v3, v3, v128
	v_rcp_f32_e32 v9, v7
	v_div_scale_f32 v10, vcc, v128, v3, v128
	v_fma_f32 v11, -v7, v9, 1.0
	v_fmac_f32_e32 v9, v11, v9
	v_mul_f32_e32 v11, v10, v9
	v_fma_f32 v12, -v7, v11, v10
	v_fmac_f32_e32 v11, v12, v9
	v_fma_f32 v7, -v7, v11, v10
	v_div_fmas_f32 v7, v7, v9, v11
	v_div_fixup_f32 v2, v7, v3, v128
	ds_write_b32 v5, v2 offset:7168
	v_mul_f32_e32 v3, 0xbfb8aa3b, v129
	v_exp_f32_e32 v3, v3
	s_nop 0
	v_add_f32_e32 v3, 1.0, v3
	v_div_scale_f32 v7, s[44:45], v3, v3, v129
	v_rcp_f32_e32 v9, v7
	v_div_scale_f32 v10, vcc, v129, v3, v129
	v_fma_f32 v11, -v7, v9, 1.0
	v_fmac_f32_e32 v9, v11, v9
	v_mul_f32_e32 v11, v10, v9
	v_fma_f32 v12, -v7, v11, v10
	v_fmac_f32_e32 v11, v12, v9
	v_fma_f32 v7, -v7, v11, v10
	v_div_fmas_f32 v7, v7, v9, v11
	v_div_fixup_f32 v2, v7, v3, v129
	ds_write_b32 v5, v2 offset:7424
	v_mul_f32_e32 v3, 0xbfb8aa3b, v130
	v_exp_f32_e32 v3, v3
	s_nop 0
	v_add_f32_e32 v3, 1.0, v3
	v_div_scale_f32 v7, s[44:45], v3, v3, v130
	v_rcp_f32_e32 v9, v7
	v_div_scale_f32 v10, vcc, v130, v3, v130
	v_fma_f32 v11, -v7, v9, 1.0
	v_fmac_f32_e32 v9, v11, v9
	v_mul_f32_e32 v11, v10, v9
	v_fma_f32 v12, -v7, v11, v10
	v_fmac_f32_e32 v11, v12, v9
	v_fma_f32 v7, -v7, v11, v10
	v_div_fmas_f32 v7, v7, v9, v11
	v_div_fixup_f32 v2, v7, v3, v130
	ds_write_b32 v5, v2 offset:7680
	v_mul_f32_e32 v3, 0xbfb8aa3b, v131
	v_exp_f32_e32 v3, v3
	s_nop 0
	v_add_f32_e32 v3, 1.0, v3
	v_div_scale_f32 v7, s[44:45], v3, v3, v131
	v_rcp_f32_e32 v9, v7
	v_div_scale_f32 v10, vcc, v131, v3, v131
	v_fma_f32 v11, -v7, v9, 1.0
	v_fmac_f32_e32 v9, v11, v9
	v_mul_f32_e32 v11, v10, v9
	v_fma_f32 v12, -v7, v11, v10
	v_fmac_f32_e32 v11, v12, v9
	v_fma_f32 v7, -v7, v11, v10
	v_div_fmas_f32 v7, v7, v9, v11
	v_div_fixup_f32 v2, v7, v3, v131
	ds_write_b32 v5, v2 offset:7936
	v_mul_f32_e32 v3, 0xbfb8aa3b, v132
	v_exp_f32_e32 v3, v3
	s_nop 0
	v_add_f32_e32 v3, 1.0, v3
	v_div_scale_f32 v7, s[44:45], v3, v3, v132
	v_rcp_f32_e32 v9, v7
	v_div_scale_f32 v10, vcc, v132, v3, v132
	v_fma_f32 v11, -v7, v9, 1.0
	v_fmac_f32_e32 v9, v11, v9
	v_mul_f32_e32 v11, v10, v9
	v_fma_f32 v12, -v7, v11, v10
	v_fmac_f32_e32 v11, v12, v9
	v_fma_f32 v7, -v7, v11, v10
	v_div_fmas_f32 v7, v7, v9, v11
	v_div_fixup_f32 v2, v7, v3, v132
	ds_write_b32 v5, v2 offset:8192
	v_mul_f32_e32 v3, 0xbfb8aa3b, v133
	v_exp_f32_e32 v3, v3
	s_nop 0
	v_add_f32_e32 v3, 1.0, v3
	v_div_scale_f32 v7, s[44:45], v3, v3, v133
	v_rcp_f32_e32 v9, v7
	v_div_scale_f32 v10, vcc, v133, v3, v133
	v_fma_f32 v11, -v7, v9, 1.0
	v_fmac_f32_e32 v9, v11, v9
	v_mul_f32_e32 v11, v10, v9
	v_fma_f32 v12, -v7, v11, v10
	v_fmac_f32_e32 v11, v12, v9
	v_fma_f32 v7, -v7, v11, v10
	v_div_fmas_f32 v7, v7, v9, v11
	v_div_fixup_f32 v2, v7, v3, v133
	ds_write_b32 v5, v2 offset:8448
	v_mul_f32_e32 v3, 0xbfb8aa3b, v134
	v_exp_f32_e32 v3, v3
	s_nop 0
	v_add_f32_e32 v3, 1.0, v3
	v_div_scale_f32 v7, s[44:45], v3, v3, v134
	v_rcp_f32_e32 v9, v7
	v_div_scale_f32 v10, vcc, v134, v3, v134
	v_fma_f32 v11, -v7, v9, 1.0
	v_fmac_f32_e32 v9, v11, v9
	v_mul_f32_e32 v11, v10, v9
	v_fma_f32 v12, -v7, v11, v10
	v_fmac_f32_e32 v11, v12, v9
	v_fma_f32 v7, -v7, v11, v10
	v_div_fmas_f32 v7, v7, v9, v11
	v_div_fixup_f32 v2, v7, v3, v134
	ds_write_b32 v5, v2 offset:8704
	v_mul_f32_e32 v3, 0xbfb8aa3b, v135
	v_exp_f32_e32 v3, v3
	s_nop 0
	v_add_f32_e32 v3, 1.0, v3
	v_div_scale_f32 v7, s[44:45], v3, v3, v135
	v_rcp_f32_e32 v9, v7
	v_div_scale_f32 v10, vcc, v135, v3, v135
	v_fma_f32 v11, -v7, v9, 1.0
	v_fmac_f32_e32 v9, v11, v9
	v_mul_f32_e32 v11, v10, v9
	v_fma_f32 v12, -v7, v11, v10
	v_fmac_f32_e32 v11, v12, v9
; __device__ __forceinline__ void phase0(const Params& p, char* smem) {
;     ...
;           float cv = b < 32 ? p.c[b * 1024 + kbase + k] : p.c_ctx[kbase + k];
;           scw[i] = cv / (1.f + __expf(-cv));
	v_fma_f32 v7, -v7, v11, v10
	v_div_fmas_f32 v7, v7, v9, v11
	v_div_fixup_f32 v2, v7, v3, v135
	ds_write_b32 v5, v2 offset:8960
	v_mul_f32_e32 v3, 0xbfb8aa3b, v136
	v_exp_f32_e32 v3, v3
	s_nop 0
	v_add_f32_e32 v3, 1.0, v3
	v_div_scale_f32 v7, s[44:45], v3, v3, v136
	v_rcp_f32_e32 v9, v7
	v_div_scale_f32 v10, vcc, v136, v3, v136
	v_fma_f32 v11, -v7, v9, 1.0
	v_fmac_f32_e32 v9, v11, v9
	v_mul_f32_e32 v11, v10, v9
	v_fma_f32 v12, -v7, v11, v10
	v_fmac_f32_e32 v11, v12, v9
	v_fma_f32 v7, -v7, v11, v10
	v_div_fmas_f32 v7, v7, v9, v11
	v_div_fixup_f32 v2, v7, v3, v136
	ds_write_b32 v5, v2 offset:9216
	v_mul_f32_e32 v3, 0xbfb8aa3b, v137
	v_exp_f32_e32 v3, v3
	s_nop 0
	v_add_f32_e32 v3, 1.0, v3
	v_div_scale_f32 v7, s[44:45], v3, v3, v137
	v_rcp_f32_e32 v9, v7
	v_div_scale_f32 v10, vcc, v137, v3, v137
	v_fma_f32 v11, -v7, v9, 1.0
	v_fmac_f32_e32 v9, v11, v9
	v_mul_f32_e32 v11, v10, v9
	v_fma_f32 v12, -v7, v11, v10
	v_fmac_f32_e32 v11, v12, v9
	v_fma_f32 v7, -v7, v11, v10
	v_div_fmas_f32 v7, v7, v9, v11
	v_div_fixup_f32 v2, v7, v3, v137
	ds_write_b32 v5, v2 offset:9472
	v_mul_f32_e32 v3, 0xbfb8aa3b, v138
	v_exp_f32_e32 v3, v3
	s_nop 0
	v_add_f32_e32 v3, 1.0, v3
	v_div_scale_f32 v7, s[44:45], v3, v3, v138
	v_rcp_f32_e32 v9, v7
	v_div_scale_f32 v10, vcc, v138, v3, v138
	v_fma_f32 v11, -v7, v9, 1.0
	v_fmac_f32_e32 v9, v11, v9
	v_mul_f32_e32 v11, v10, v9
	v_fma_f32 v12, -v7, v11, v10
	v_fmac_f32_e32 v11, v12, v9
	v_fma_f32 v7, -v7, v11, v10
	v_div_fmas_f32 v7, v7, v9, v11
	v_div_fixup_f32 v2, v7, v3, v138
	ds_write_b32 v5, v2 offset:9728
	v_mul_f32_e32 v3, 0xbfb8aa3b, v139
	v_exp_f32_e32 v3, v3
	s_nop 0
	v_add_f32_e32 v3, 1.0, v3
	v_div_scale_f32 v7, s[44:45], v3, v3, v139
	v_rcp_f32_e32 v9, v7
	v_div_scale_f32 v10, vcc, v139, v3, v139
	v_fma_f32 v11, -v7, v9, 1.0
	v_fmac_f32_e32 v9, v11, v9
	v_mul_f32_e32 v11, v10, v9
	v_fma_f32 v12, -v7, v11, v10
	v_fmac_f32_e32 v11, v12, v9
	v_fma_f32 v7, -v7, v11, v10
	v_div_fmas_f32 v7, v7, v9, v11
	v_div_fixup_f32 v2, v7, v3, v139
	ds_write_b32 v5, v2 offset:9984
	v_mul_f32_e32 v3, 0xbfb8aa3b, v140
	v_exp_f32_e32 v3, v3
	s_nop 0
	v_add_f32_e32 v3, 1.0, v3
	v_div_scale_f32 v7, s[44:45], v3, v3, v140
	v_rcp_f32_e32 v9, v7
	v_div_scale_f32 v10, vcc, v140, v3, v140
	v_fma_f32 v11, -v7, v9, 1.0
	v_fmac_f32_e32 v9, v11, v9
	v_mul_f32_e32 v11, v10, v9
	v_fma_f32 v12, -v7, v11, v10
	v_fmac_f32_e32 v11, v12, v9
	v_fma_f32 v7, -v7, v11, v10
	v_div_fmas_f32 v7, v7, v9, v11
	v_div_fixup_f32 v2, v7, v3, v140
	ds_write_b32 v5, v2 offset:10240
	v_mul_f32_e32 v3, 0xbfb8aa3b, v141
	v_exp_f32_e32 v3, v3
	s_nop 0
	v_add_f32_e32 v3, 1.0, v3
	v_div_scale_f32 v7, s[44:45], v3, v3, v141
	v_rcp_f32_e32 v9, v7
	v_div_scale_f32 v10, vcc, v141, v3, v141
	v_fma_f32 v11, -v7, v9, 1.0
	v_fmac_f32_e32 v9, v11, v9
	v_mul_f32_e32 v11, v10, v9
	v_fma_f32 v12, -v7, v11, v10
	v_fmac_f32_e32 v11, v12, v9
	v_fma_f32 v7, -v7, v11, v10
	v_div_fmas_f32 v7, v7, v9, v11
	v_div_fixup_f32 v2, v7, v3, v141
	ds_write_b32 v5, v2 offset:10496
	v_mul_f32_e32 v3, 0xbfb8aa3b, v142
	v_exp_f32_e32 v3, v3
	s_nop 0
	v_add_f32_e32 v3, 1.0, v3
	v_div_scale_f32 v7, s[44:45], v3, v3, v142
	v_rcp_f32_e32 v9, v7
	v_div_scale_f32 v10, vcc, v142, v3, v142
	v_fma_f32 v11, -v7, v9, 1.0
	v_fmac_f32_e32 v9, v11, v9
	v_mul_f32_e32 v11, v10, v9
	v_fma_f32 v12, -v7, v11, v10
	v_fmac_f32_e32 v11, v12, v9
	v_fma_f32 v7, -v7, v11, v10
	v_div_fmas_f32 v7, v7, v9, v11
	v_div_fixup_f32 v2, v7, v3, v142
	ds_write_b32 v5, v2 offset:10752
	v_mul_f32_e32 v3, 0xbfb8aa3b, v143
	v_exp_f32_e32 v3, v3
	s_nop 0
	v_add_f32_e32 v3, 1.0, v3
	v_div_scale_f32 v7, s[44:45], v3, v3, v143
	v_rcp_f32_e32 v9, v7
	v_div_scale_f32 v10, vcc, v143, v3, v143
	v_fma_f32 v11, -v7, v9, 1.0
	v_fmac_f32_e32 v9, v11, v9
	v_mul_f32_e32 v11, v10, v9
	v_fma_f32 v12, -v7, v11, v10
	v_fmac_f32_e32 v11, v12, v9
	v_fma_f32 v7, -v7, v11, v10
	v_div_fmas_f32 v7, v7, v9, v11
	v_div_fixup_f32 v2, v7, v3, v143
	ds_write_b32 v5, v2 offset:11008
	v_mul_f32_e32 v3, 0xbfb8aa3b, v144
	v_exp_f32_e32 v3, v3
	s_nop 0
	v_add_f32_e32 v3, 1.0, v3
	v_div_scale_f32 v7, s[44:45], v3, v3, v144
	v_rcp_f32_e32 v9, v7
	v_div_scale_f32 v10, vcc, v144, v3, v144
	v_fma_f32 v11, -v7, v9, 1.0
	v_fmac_f32_e32 v9, v11, v9
	v_mul_f32_e32 v11, v10, v9
	v_fma_f32 v12, -v7, v11, v10
	v_fmac_f32_e32 v11, v12, v9
	v_fma_f32 v7, -v7, v11, v10
	v_div_fmas_f32 v7, v7, v9, v11
	v_div_fixup_f32 v2, v7, v3, v144
	ds_write_b32 v5, v2 offset:11264
	v_mul_f32_e32 v3, 0xbfb8aa3b, v145
	v_exp_f32_e32 v3, v3
	s_nop 0
	v_add_f32_e32 v3, 1.0, v3
	v_div_scale_f32 v7, s[44:45], v3, v3, v145
	v_rcp_f32_e32 v9, v7
	v_div_scale_f32 v10, vcc, v145, v3, v145
	v_fma_f32 v11, -v7, v9, 1.0
	v_fmac_f32_e32 v9, v11, v9
	v_mul_f32_e32 v11, v10, v9
	v_fma_f32 v12, -v7, v11, v10
	v_fmac_f32_e32 v11, v12, v9
	v_fma_f32 v7, -v7, v11, v10
	v_div_fmas_f32 v7, v7, v9, v11
	v_div_fixup_f32 v2, v7, v3, v145
	ds_write_b32 v5, v2 offset:11520
	v_mul_f32_e32 v3, 0xbfb8aa3b, v146
	v_exp_f32_e32 v3, v3
	s_nop 0
	v_add_f32_e32 v3, 1.0, v3
	v_div_scale_f32 v7, s[44:45], v3, v3, v146
	v_rcp_f32_e32 v9, v7
	v_div_scale_f32 v10, vcc, v146, v3, v146
	v_fma_f32 v11, -v7, v9, 1.0
	v_fmac_f32_e32 v9, v11, v9
	v_mul_f32_e32 v11, v10, v9
	v_fma_f32 v12, -v7, v11, v10
	v_fmac_f32_e32 v11, v12, v9
	v_fma_f32 v7, -v7, v11, v10
	v_div_fmas_f32 v7, v7, v9, v11
	v_div_fixup_f32 v2, v7, v3, v146
	ds_write_b32 v5, v2 offset:11776
	v_mul_f32_e32 v3, 0xbfb8aa3b, v147
	v_exp_f32_e32 v3, v3
	s_nop 0
	v_add_f32_e32 v3, 1.0, v3
	v_div_scale_f32 v7, s[44:45], v3, v3, v147
	v_rcp_f32_e32 v9, v7
	v_div_scale_f32 v10, vcc, v147, v3, v147
	v_fma_f32 v11, -v7, v9, 1.0
	v_fmac_f32_e32 v9, v11, v9
	v_mul_f32_e32 v11, v10, v9
; __device__ __forceinline__ void phase0(const Params& p, char* smem) {
;     ...
;           float cv = b < 32 ? p.c[b * 1024 + kbase + k] : p.c_ctx[kbase + k];
;           scw[i] = cv / (1.f + __expf(-cv));
	v_fma_f32 v12, -v7, v11, v10
	v_fmac_f32_e32 v11, v12, v9
	v_fma_f32 v7, -v7, v11, v10
	v_div_fmas_f32 v7, v7, v9, v11
	v_div_fixup_f32 v2, v7, v3, v147
	ds_write_b32 v5, v2 offset:12032
	v_mul_f32_e32 v3, 0xbfb8aa3b, v148
	v_exp_f32_e32 v3, v3
	s_nop 0
	v_add_f32_e32 v3, 1.0, v3
	v_div_scale_f32 v7, s[44:45], v3, v3, v148
	v_rcp_f32_e32 v9, v7
	v_div_scale_f32 v10, vcc, v148, v3, v148
	v_fma_f32 v11, -v7, v9, 1.0
	v_fmac_f32_e32 v9, v11, v9
	v_mul_f32_e32 v11, v10, v9
	v_fma_f32 v12, -v7, v11, v10
	v_fmac_f32_e32 v11, v12, v9
	v_fma_f32 v7, -v7, v11, v10
	v_div_fmas_f32 v7, v7, v9, v11
	v_div_fixup_f32 v2, v7, v3, v148
	ds_write_b32 v5, v2 offset:12288
	v_mul_f32_e32 v3, 0xbfb8aa3b, v149
	v_exp_f32_e32 v3, v3
	s_nop 0
	v_add_f32_e32 v3, 1.0, v3
	v_div_scale_f32 v7, s[44:45], v3, v3, v149
	v_rcp_f32_e32 v9, v7
	v_div_scale_f32 v10, vcc, v149, v3, v149
	v_fma_f32 v11, -v7, v9, 1.0
	v_fmac_f32_e32 v9, v11, v9
	v_mul_f32_e32 v11, v10, v9
	v_fma_f32 v12, -v7, v11, v10
	v_fmac_f32_e32 v11, v12, v9
	v_fma_f32 v7, -v7, v11, v10
	v_div_fmas_f32 v7, v7, v9, v11
	v_div_fixup_f32 v2, v7, v3, v149
	ds_write_b32 v5, v2 offset:12544
	v_mul_f32_e32 v3, 0xbfb8aa3b, v150
	v_exp_f32_e32 v3, v3
	s_nop 0
	v_add_f32_e32 v3, 1.0, v3
	v_div_scale_f32 v7, s[44:45], v3, v3, v150
	v_rcp_f32_e32 v9, v7
	v_div_scale_f32 v10, vcc, v150, v3, v150
	v_fma_f32 v11, -v7, v9, 1.0
	v_fmac_f32_e32 v9, v11, v9
	v_mul_f32_e32 v11, v10, v9
	v_fma_f32 v12, -v7, v11, v10
	v_fmac_f32_e32 v11, v12, v9
	v_fma_f32 v7, -v7, v11, v10
	v_div_fmas_f32 v7, v7, v9, v11
	v_div_fixup_f32 v2, v7, v3, v150
	ds_write_b32 v5, v2 offset:12800
	v_mul_f32_e32 v3, 0xbfb8aa3b, v151
	v_exp_f32_e32 v3, v3
	s_nop 0
	v_add_f32_e32 v3, 1.0, v3
	v_div_scale_f32 v7, s[44:45], v3, v3, v151
	v_rcp_f32_e32 v9, v7
	v_div_scale_f32 v10, vcc, v151, v3, v151
	v_fma_f32 v11, -v7, v9, 1.0
	v_fmac_f32_e32 v9, v11, v9
	v_mul_f32_e32 v11, v10, v9
	v_fma_f32 v12, -v7, v11, v10
	v_fmac_f32_e32 v11, v12, v9
	v_fma_f32 v7, -v7, v11, v10
	v_div_fmas_f32 v7, v7, v9, v11
	v_div_fixup_f32 v2, v7, v3, v151
	ds_write_b32 v5, v2 offset:13056
	v_mul_f32_e32 v3, 0xbfb8aa3b, v152
	v_exp_f32_e32 v3, v3
	s_nop 0
	v_add_f32_e32 v3, 1.0, v3
	v_div_scale_f32 v7, s[44:45], v3, v3, v152
	v_rcp_f32_e32 v9, v7
	v_div_scale_f32 v10, vcc, v152, v3, v152
	v_fma_f32 v11, -v7, v9, 1.0
	v_fmac_f32_e32 v9, v11, v9
	v_mul_f32_e32 v11, v10, v9
	v_fma_f32 v12, -v7, v11, v10
	v_fmac_f32_e32 v11, v12, v9
	v_fma_f32 v7, -v7, v11, v10
	v_div_fmas_f32 v7, v7, v9, v11
	v_div_fixup_f32 v2, v7, v3, v152
	ds_write_b32 v5, v2 offset:13312
	v_mul_f32_e32 v3, 0xbfb8aa3b, v153
	v_exp_f32_e32 v3, v3
	s_nop 0
	v_add_f32_e32 v3, 1.0, v3
	v_div_scale_f32 v7, s[44:45], v3, v3, v153
	v_rcp_f32_e32 v9, v7
	v_div_scale_f32 v10, vcc, v153, v3, v153
	v_fma_f32 v11, -v7, v9, 1.0
	v_fmac_f32_e32 v9, v11, v9
	v_mul_f32_e32 v11, v10, v9
	v_fma_f32 v12, -v7, v11, v10
	v_fmac_f32_e32 v11, v12, v9
	v_fma_f32 v7, -v7, v11, v10
	v_div_fmas_f32 v7, v7, v9, v11
	v_div_fixup_f32 v2, v7, v3, v153
	ds_write_b32 v5, v2 offset:13568
	v_mul_f32_e32 v3, 0xbfb8aa3b, v154
	v_exp_f32_e32 v3, v3
	s_nop 0
	v_add_f32_e32 v3, 1.0, v3
	v_div_scale_f32 v7, s[44:45], v3, v3, v154
	v_rcp_f32_e32 v9, v7
	v_div_scale_f32 v10, vcc, v154, v3, v154
	v_fma_f32 v11, -v7, v9, 1.0
	v_fmac_f32_e32 v9, v11, v9
	v_mul_f32_e32 v11, v10, v9
	v_fma_f32 v12, -v7, v11, v10
	v_fmac_f32_e32 v11, v12, v9
	v_fma_f32 v7, -v7, v11, v10
	v_div_fmas_f32 v7, v7, v9, v11
	v_div_fixup_f32 v2, v7, v3, v154
	ds_write_b32 v5, v2 offset:13824
	v_mul_f32_e32 v3, 0xbfb8aa3b, v155
	v_exp_f32_e32 v3, v3
	s_nop 0
	v_add_f32_e32 v3, 1.0, v3
	v_div_scale_f32 v7, s[44:45], v3, v3, v155
	v_rcp_f32_e32 v9, v7
	v_div_scale_f32 v10, vcc, v155, v3, v155
	v_fma_f32 v11, -v7, v9, 1.0
	v_fmac_f32_e32 v9, v11, v9
	v_mul_f32_e32 v11, v10, v9
	v_fma_f32 v12, -v7, v11, v10
	v_fmac_f32_e32 v11, v12, v9
	v_fma_f32 v7, -v7, v11, v10
	v_div_fmas_f32 v7, v7, v9, v11
	v_div_fixup_f32 v2, v7, v3, v155
	ds_write_b32 v5, v2 offset:14080
	v_mul_f32_e32 v3, 0xbfb8aa3b, v156
	v_exp_f32_e32 v3, v3
	s_nop 0
	v_add_f32_e32 v3, 1.0, v3
	v_div_scale_f32 v7, s[44:45], v3, v3, v156
	v_rcp_f32_e32 v9, v7
	v_div_scale_f32 v10, vcc, v156, v3, v156
	v_fma_f32 v11, -v7, v9, 1.0
	v_fmac_f32_e32 v9, v11, v9
	v_mul_f32_e32 v11, v10, v9
	v_fma_f32 v12, -v7, v11, v10
	v_fmac_f32_e32 v11, v12, v9
	v_fma_f32 v7, -v7, v11, v10
; __device__ __forceinline__ void phase0(const Params& p, char* smem) {
;     ...
;           float cv = b < 32 ? p.c[b * 1024 + kbase + k] : p.c_ctx[kbase + k];
;           scw[i] = cv / (1.f + __expf(-cv));
	v_div_fmas_f32 v7, v7, v9, v11
	v_div_fixup_f32 v2, v7, v3, v156
	ds_write_b32 v5, v2 offset:14336
	v_mul_f32_e32 v3, 0xbfb8aa3b, v157
	v_exp_f32_e32 v3, v3
	s_nop 0
	v_add_f32_e32 v3, 1.0, v3
	v_div_scale_f32 v7, s[44:45], v3, v3, v157
	v_rcp_f32_e32 v9, v7
	v_div_scale_f32 v10, vcc, v157, v3, v157
	v_fma_f32 v11, -v7, v9, 1.0
	v_fmac_f32_e32 v9, v11, v9
	v_mul_f32_e32 v11, v10, v9
	v_fma_f32 v12, -v7, v11, v10
	v_fmac_f32_e32 v11, v12, v9
	v_fma_f32 v7, -v7, v11, v10
	v_div_fmas_f32 v7, v7, v9, v11
	v_div_fixup_f32 v2, v7, v3, v157
	ds_write_b32 v5, v2 offset:14592
	v_mul_f32_e32 v3, 0xbfb8aa3b, v158
	v_exp_f32_e32 v3, v3
	s_nop 0
	v_add_f32_e32 v3, 1.0, v3
	v_div_scale_f32 v7, s[44:45], v3, v3, v158
	v_rcp_f32_e32 v9, v7
	v_div_scale_f32 v10, vcc, v158, v3, v158
	v_fma_f32 v11, -v7, v9, 1.0
	v_fmac_f32_e32 v9, v11, v9
	v_mul_f32_e32 v11, v10, v9
	v_fma_f32 v12, -v7, v11, v10
	v_fmac_f32_e32 v11, v12, v9
	v_fma_f32 v7, -v7, v11, v10
	v_div_fmas_f32 v7, v7, v9, v11
	v_div_fixup_f32 v2, v7, v3, v158
	ds_write_b32 v5, v2 offset:14848
	v_mul_f32_e32 v3, 0xbfb8aa3b, v159
	v_exp_f32_e32 v3, v3
	s_nop 0
	v_add_f32_e32 v3, 1.0, v3
	v_div_scale_f32 v7, s[44:45], v3, v3, v159
	v_rcp_f32_e32 v9, v7
	v_div_scale_f32 v10, vcc, v159, v3, v159
	v_fma_f32 v11, -v7, v9, 1.0
	v_fmac_f32_e32 v9, v11, v9
	v_mul_f32_e32 v11, v10, v9
	v_fma_f32 v12, -v7, v11, v10
	v_fmac_f32_e32 v11, v12, v9
	v_fma_f32 v7, -v7, v11, v10
	v_div_fmas_f32 v7, v7, v9, v11
	v_div_fixup_f32 v2, v7, v3, v159
	ds_write_b32 v5, v2 offset:15104
	v_mul_f32_e32 v3, 0xbfb8aa3b, v160
	v_exp_f32_e32 v3, v3
	s_nop 0
	v_add_f32_e32 v3, 1.0, v3
	v_div_scale_f32 v7, s[44:45], v3, v3, v160
	v_rcp_f32_e32 v9, v7
	v_div_scale_f32 v10, vcc, v160, v3, v160
	v_fma_f32 v11, -v7, v9, 1.0
	v_fmac_f32_e32 v9, v11, v9
	v_mul_f32_e32 v11, v10, v9
	v_fma_f32 v12, -v7, v11, v10
	v_fmac_f32_e32 v11, v12, v9
	v_fma_f32 v7, -v7, v11, v10
	v_div_fmas_f32 v7, v7, v9, v11
	v_div_fixup_f32 v2, v7, v3, v160
	ds_write_b32 v5, v2 offset:15360
	v_mul_f32_e32 v3, 0xbfb8aa3b, v161
	v_exp_f32_e32 v3, v3
	s_nop 0
	v_add_f32_e32 v3, 1.0, v3
	v_div_scale_f32 v7, s[44:45], v3, v3, v161
	v_rcp_f32_e32 v9, v7
	v_div_scale_f32 v10, vcc, v161, v3, v161
	v_fma_f32 v11, -v7, v9, 1.0
	v_fmac_f32_e32 v9, v11, v9
	v_mul_f32_e32 v11, v10, v9
	v_fma_f32 v12, -v7, v11, v10
	v_fmac_f32_e32 v11, v12, v9
	v_fma_f32 v7, -v7, v11, v10
	v_div_fmas_f32 v7, v7, v9, v11
	v_div_fixup_f32 v2, v7, v3, v161
	ds_write_b32 v5, v2 offset:15616
	v_mul_f32_e32 v3, 0xbfb8aa3b, v162
	v_exp_f32_e32 v3, v3
	s_nop 0
	v_add_f32_e32 v3, 1.0, v3
	v_div_scale_f32 v7, s[44:45], v3, v3, v162
	v_rcp_f32_e32 v9, v7
	v_div_scale_f32 v10, vcc, v162, v3, v162
	v_fma_f32 v11, -v7, v9, 1.0
	v_fmac_f32_e32 v9, v11, v9
	v_mul_f32_e32 v11, v10, v9
	v_fma_f32 v12, -v7, v11, v10
	v_fmac_f32_e32 v11, v12, v9
	v_fma_f32 v7, -v7, v11, v10
	v_div_fmas_f32 v7, v7, v9, v11
	v_div_fixup_f32 v2, v7, v3, v162
	ds_write_b32 v5, v2 offset:15872
	v_mul_f32_e32 v3, 0xbfb8aa3b, v163
	v_exp_f32_e32 v3, v3
	s_nop 0
	v_add_f32_e32 v3, 1.0, v3
	v_div_scale_f32 v7, s[44:45], v3, v3, v163
	v_rcp_f32_e32 v9, v7
	v_div_scale_f32 v10, vcc, v163, v3, v163
	v_fma_f32 v11, -v7, v9, 1.0
	v_fmac_f32_e32 v9, v11, v9
	v_mul_f32_e32 v11, v10, v9
	v_fma_f32 v12, -v7, v11, v10
	v_fmac_f32_e32 v11, v12, v9
	v_fma_f32 v7, -v7, v11, v10
	v_div_fmas_f32 v7, v7, v9, v11
	v_div_fixup_f32 v2, v7, v3, v163
	ds_write_b32 v5, v2 offset:16128
	v_mul_f32_e32 v3, 0xbfb8aa3b, v164
	v_exp_f32_e32 v3, v3
	s_nop 0
	v_add_f32_e32 v3, 1.0, v3
	v_div_scale_f32 v7, s[44:45], v3, v3, v164
	v_rcp_f32_e32 v9, v7
	v_div_scale_f32 v10, vcc, v164, v3, v164
	v_fma_f32 v11, -v7, v9, 1.0
	v_fmac_f32_e32 v9, v11, v9
	v_mul_f32_e32 v11, v10, v9
	v_fma_f32 v12, -v7, v11, v10
	v_fmac_f32_e32 v11, v12, v9
	v_fma_f32 v7, -v7, v11, v10
	v_div_fmas_f32 v7, v7, v9, v11
	v_div_fixup_f32 v2, v7, v3, v164
	ds_write_b32 v5, v2 offset:16384
	v_mul_f32_e32 v3, 0xbfb8aa3b, v165
	v_exp_f32_e32 v3, v3
	s_nop 0
	v_add_f32_e32 v3, 1.0, v3
	v_div_scale_f32 v7, s[44:45], v3, v3, v165
	v_rcp_f32_e32 v9, v7
	v_div_scale_f32 v10, vcc, v165, v3, v165
	v_fma_f32 v11, -v7, v9, 1.0
	v_fmac_f32_e32 v9, v11, v9
	v_mul_f32_e32 v11, v10, v9
	v_fma_f32 v12, -v7, v11, v10
	v_fmac_f32_e32 v11, v12, v9
	v_fma_f32 v7, -v7, v11, v10
	v_div_fmas_f32 v7, v7, v9, v11
	v_div_fixup_f32 v2, v7, v3, v165
	ds_write_b32 v5, v2 offset:16640
